# speedup vs baseline: 1.0053x; 1.0053x over previous
.Lh2_137:
	s_or_b64 exec, exec, s[28:29]
	v_mov_b32_e32 v196, v129
	v_mov_b32_e32 v2, v130
	s_waitcnt vmcnt(2)
	s_barrier
	s_add_i32 s28, s62, 0x18000
	v_lshl_add_u64 v[4:5], s[8:9], 0, v[196:197]
	v_mov_b32_e32 v3, v197
	v_lshl_add_u64 v[4:5], v[4:5], 0, s[94:95]
	s_mov_b32 m0, s28
	v_lshl_add_u64 v[2:3], s[8:9], 0, v[2:3]
	s_add_i32 s29, s62, 0x1a000
	global_load_lds_dwordx4 v[4:5], off
	v_lshl_add_u64 v[2:3], v[2:3], 0, s[94:95]
	s_mov_b32 m0, s29
	v_mov_b32_e32 v196, v129
	global_load_lds_dwordx4 v[2:3], off
	v_mov_b32_e32 v2, v130
	s_add_i32 s72, s62, 0x8000
	v_lshl_add_u64 v[4:5], s[10:11], 0, v[196:197]
	v_mov_b32_e32 v3, v197
	v_lshl_add_u64 v[4:5], v[4:5], 0, s[94:95]
	s_mov_b32 m0, s72
	v_lshl_add_u64 v[2:3], s[10:11], 0, v[2:3]
	s_add_i32 s73, s62, 0xa000
	global_load_lds_dwordx4 v[4:5], off
	v_lshl_add_u64 v[2:3], v[2:3], 0, s[94:95]
	s_mov_b32 m0, s73
	v_mov_b32_e32 v196, v129
	global_load_lds_dwordx4 v[2:3], off
	v_mov_b32_e32 v2, v130
	s_add_i32 s33, s62, 0x1c000
	v_lshl_add_u64 v[4:5], s[6:7], 0, v[196:197]
	v_mov_b32_e32 v3, v197
	v_lshl_add_u64 v[4:5], v[4:5], 0, s[94:95]
	s_mov_b32 m0, s33
	v_lshl_add_u64 v[2:3], s[6:7], 0, v[2:3]
	s_add_i32 s74, s62, 0x1e000
	global_load_lds_dwordx4 v[4:5], off
	v_lshl_add_u64 v[2:3], v[2:3], 0, s[94:95]
	s_mov_b32 m0, s74
	v_and_b32_e32 v6, 15, v128
	global_load_lds_dwordx4 v[2:3], off
	v_and_b32_e32 v7, 48, v128
	v_lshlrev_b32_e32 v2, 6, v6
	v_lshlrev_b32_e32 v4, 2, v128
	v_or_b32_e32 v3, v2, v7
	v_and_b32_e32 v4, 32, v4
	s_mov_b32 s6, 0x10000
	v_bitop3_b32 v5, v3, s6, v4 bitop3:0xde
	s_mov_b32 s6, 0x14000
	v_lshlrev_b32_e32 v9, 13, v0
	v_lshlrev_b32_e32 v0, 6, v128
	s_waitcnt vmcnt(6)
	v_lshlrev_b32_e32 v1, 12, v1
	v_bitop3_b32 v6, v3, s6, v4 bitop3:0xde
	s_mov_b32 s6, 0x1c000
	v_and_b32_e32 v0, 0x3c0, v0
	v_readlane_b32 s44, v253, 1
	v_and_b32_e32 v1, 0x3000, v1
	v_bitop3_b32 v2, v2, v4, v7 bitop3:0x36
	v_bitop3_b32 v8, v3, s2, v4 bitop3:0xde
	v_bitop3_b32 v3, v3, s6, v4 bitop3:0xde
	v_bitop3_b32 v4, v0, v4, v7 bitop3:0x36
	v_or_b32_e32 v7, 0x800, v9
	v_or_b32_e32 v10, 0x1000, v9
	v_or_b32_e32 v11, 0x1800, v9
	s_add_u32 s36, s54, s36
	v_mov_b32_e32 v0, 0
	v_readlane_b32 s45, v253, 2
	v_readlane_b32 s46, v253, 3
	v_readlane_b32 s47, v253, 4
	v_readlane_b32 s48, v253, 5
	v_readlane_b32 s49, v253, 6
	v_readlane_b32 s50, v253, 7
	v_readlane_b32 s51, v253, 8
	s_addc_u32 s37, s34, s37
	s_mov_b32 s38, -2
	s_add_i32 s76, s62, 0xc000
	s_add_i32 s75, s62, 0xe000
	v_add_u32_e32 v138, v5, v1
	v_add_u32_e32 v134, v2, v9
	v_add_u32_e32 v133, v4, v7
	v_add_u32_e32 v132, v4, v10
	v_add_u32_e32 v131, v4, v11
	v_add_u32_e32 v137, v6, v1
	v_add_u32_e32 v136, v8, v1
	v_add_u32_e32 v135, v3, v1
	s_mov_b64 s[6:7], s[50:51]
	v_mov_b32_e32 v1, v0
	v_mov_b32_e32 v2, v0
	v_mov_b32_e32 v3, v0
	v_mov_b32_e32 v4, v0
	v_mov_b32_e32 v5, v0
	v_mov_b32_e32 v6, v0
	v_mov_b32_e32 v7, v0
	v_mov_b32_e32 v8, v0
	v_mov_b32_e32 v9, v0
	v_mov_b32_e32 v10, v0
	v_mov_b32_e32 v11, v0
	v_mov_b32_e32 v12, v0
	v_mov_b32_e32 v13, v0
	v_mov_b32_e32 v14, v0
	v_mov_b32_e32 v15, v0
	v_mov_b32_e32 v16, v0
	v_mov_b32_e32 v17, v0
	v_mov_b32_e32 v18, v0
	v_mov_b32_e32 v19, v0
	v_mov_b32_e32 v20, v0
	v_mov_b32_e32 v21, v0
	v_mov_b32_e32 v22, v0
	v_mov_b32_e32 v23, v0
	v_mov_b32_e32 v24, v0
	v_mov_b32_e32 v25, v0
	v_mov_b32_e32 v26, v0
	v_mov_b32_e32 v27, v0
	v_mov_b32_e32 v28, v0
	v_mov_b32_e32 v29, v0
	v_mov_b32_e32 v30, v0
	v_mov_b32_e32 v31, v0
	v_mov_b32_e32 v32, v0
	v_mov_b32_e32 v33, v0
	v_mov_b32_e32 v34, v0
	v_mov_b32_e32 v35, v0
	v_mov_b32_e32 v36, v0
	v_mov_b32_e32 v37, v0
	v_mov_b32_e32 v38, v0
	v_mov_b32_e32 v39, v0
	v_mov_b32_e32 v40, v0
	v_mov_b32_e32 v41, v0
	v_mov_b32_e32 v42, v0
	v_mov_b32_e32 v43, v0
	v_mov_b32_e32 v44, v0
	v_mov_b32_e32 v45, v0
	v_mov_b32_e32 v46, v0
	v_mov_b32_e32 v47, v0
	v_mov_b32_e32 v48, v0
	v_mov_b32_e32 v49, v0
	v_mov_b32_e32 v50, v0
	v_mov_b32_e32 v51, v0
	v_mov_b32_e32 v52, v0
	v_mov_b32_e32 v53, v0
	v_mov_b32_e32 v54, v0
	v_mov_b32_e32 v55, v0
	v_mov_b32_e32 v56, v0
	v_mov_b32_e32 v57, v0
	v_mov_b32_e32 v58, v0
	v_mov_b32_e32 v59, v0
	v_mov_b32_e32 v60, v0
	v_mov_b32_e32 v61, v0
	v_mov_b32_e32 v62, v0
	v_mov_b32_e32 v63, v0
	v_mov_b32_e32 v64, v0
	v_mov_b32_e32 v65, v0
	v_mov_b32_e32 v66, v0
	v_mov_b32_e32 v67, v0
	v_mov_b32_e32 v68, v0
	v_mov_b32_e32 v69, v0
	v_mov_b32_e32 v70, v0
	v_mov_b32_e32 v71, v0
	v_mov_b32_e32 v72, v0
	v_mov_b32_e32 v73, v0
	v_mov_b32_e32 v74, v0
	v_mov_b32_e32 v75, v0
	v_mov_b32_e32 v76, v0
	v_mov_b32_e32 v77, v0
	v_mov_b32_e32 v78, v0
	v_mov_b32_e32 v79, v0
	v_mov_b32_e32 v80, v0
	v_mov_b32_e32 v81, v0
	v_mov_b32_e32 v82, v0
	v_mov_b32_e32 v83, v0
	v_mov_b32_e32 v84, v0
	v_mov_b32_e32 v85, v0
	v_mov_b32_e32 v86, v0
	v_mov_b32_e32 v87, v0
	v_mov_b32_e32 v88, v0
	v_mov_b32_e32 v89, v0
	v_mov_b32_e32 v90, v0
	v_mov_b32_e32 v91, v0
	v_mov_b32_e32 v92, v0
	v_mov_b32_e32 v93, v0
	v_mov_b32_e32 v94, v0
	v_mov_b32_e32 v95, v0
	v_mov_b32_e32 v96, v0
	v_mov_b32_e32 v97, v0
	v_mov_b32_e32 v98, v0
	v_mov_b32_e32 v99, v0
	v_mov_b32_e32 v100, v0
	v_mov_b32_e32 v101, v0
	v_mov_b32_e32 v102, v0
	v_mov_b32_e32 v103, v0
	v_mov_b32_e32 v104, v0
	v_mov_b32_e32 v105, v0
	v_mov_b32_e32 v106, v0
	v_mov_b32_e32 v107, v0
	v_mov_b32_e32 v108, v0
	v_mov_b32_e32 v109, v0
	v_mov_b32_e32 v110, v0
	v_mov_b32_e32 v111, v0
	v_mov_b32_e32 v112, v0
	v_mov_b32_e32 v113, v0
	v_mov_b32_e32 v114, v0
	v_mov_b32_e32 v115, v0
	v_mov_b32_e32 v116, v0
	v_mov_b32_e32 v117, v0
	v_mov_b32_e32 v118, v0
	v_mov_b32_e32 v119, v0
	v_mov_b32_e32 v120, v0
	v_mov_b32_e32 v121, v0
	v_mov_b32_e32 v122, v0
	v_mov_b32_e32 v123, v0
	v_mov_b32_e32 v124, v0
	v_mov_b32_e32 v125, v0
	v_mov_b32_e32 v126, v0
	v_mov_b32_e32 v127, v0
	s_mov_b64 s[44:45], 0x20560080
	s_mov_b64 s[46:47], 0xd400100
	s_mov_b64 s[48:49], 0x20400100
	s_mov_b64 s[50:51], 0xd560100
	s_mov_b64 s[90:91], 0x20560100
	s_mov_b64 s[92:93], 0xd400180
	s_mov_b64 s[96:97], 0x20400180
	s_mov_b64 vcc, 0xd560180
	s_barrier
	.p2align	6

.LBB0_137:
	s_or_b64 exec, exec, s[28:29]
	v_mov_b32_e32 v196, v129
	v_mov_b32_e32 v2, v130
	s_waitcnt vmcnt(4)
	s_barrier
	s_add_i32 s28, s62, 0x18000
	v_lshl_add_u64 v[4:5], s[8:9], 0, v[196:197]
	v_mov_b32_e32 v3, v197
	v_lshl_add_u64 v[4:5], v[4:5], 0, s[94:95]
	s_mov_b32 m0, s28
	v_lshl_add_u64 v[2:3], s[8:9], 0, v[2:3]
	s_add_i32 s29, s62, 0x1a000
	global_load_lds_dwordx4 v[4:5], off
	v_lshl_add_u64 v[2:3], v[2:3], 0, s[94:95]
	s_mov_b32 m0, s29
	v_mov_b32_e32 v196, v129
	global_load_lds_dwordx4 v[2:3], off
	v_mov_b32_e32 v2, v130
	s_add_i32 s72, s62, 0x8000
	v_lshl_add_u64 v[4:5], s[10:11], 0, v[196:197]
	v_mov_b32_e32 v3, v197
	v_lshl_add_u64 v[4:5], v[4:5], 0, s[94:95]
	s_mov_b32 m0, s72
	v_lshl_add_u64 v[2:3], s[10:11], 0, v[2:3]
	s_add_i32 s73, s62, 0xa000
	global_load_lds_dwordx4 v[4:5], off
	v_lshl_add_u64 v[2:3], v[2:3], 0, s[94:95]
	s_mov_b32 m0, s73
	v_mov_b32_e32 v196, v129
	global_load_lds_dwordx4 v[2:3], off
	v_mov_b32_e32 v2, v130
	s_add_i32 s33, s62, 0x1c000
	v_lshl_add_u64 v[4:5], s[6:7], 0, v[196:197]
	v_mov_b32_e32 v3, v197
	v_lshl_add_u64 v[4:5], v[4:5], 0, s[94:95]
	s_mov_b32 m0, s33
	v_lshl_add_u64 v[2:3], s[6:7], 0, v[2:3]
	s_add_i32 s74, s62, 0x1e000
	global_load_lds_dwordx4 v[4:5], off
	v_lshl_add_u64 v[2:3], v[2:3], 0, s[94:95]
	s_mov_b32 m0, s74
	v_and_b32_e32 v6, 15, v128
	global_load_lds_dwordx4 v[2:3], off
	v_and_b32_e32 v7, 48, v128
	v_lshlrev_b32_e32 v2, 6, v6
	v_lshlrev_b32_e32 v4, 2, v128
	v_or_b32_e32 v3, v2, v7
	v_and_b32_e32 v4, 32, v4
	s_mov_b32 s6, 0x10000
	v_bitop3_b32 v5, v3, s6, v4 bitop3:0xde
	s_mov_b32 s6, 0x14000
	v_lshlrev_b32_e32 v9, 13, v0
	v_lshlrev_b32_e32 v0, 6, v128
	s_waitcnt vmcnt(6)
	v_lshlrev_b32_e32 v1, 12, v1
	v_bitop3_b32 v6, v3, s6, v4 bitop3:0xde
	s_mov_b32 s6, 0x1c000
	v_and_b32_e32 v0, 0x3c0, v0
	v_readlane_b32 s44, v253, 1
	v_and_b32_e32 v1, 0x3000, v1
	v_bitop3_b32 v2, v2, v4, v7 bitop3:0x36
	v_bitop3_b32 v8, v3, s2, v4 bitop3:0xde
	v_bitop3_b32 v3, v3, s6, v4 bitop3:0xde
	v_bitop3_b32 v4, v0, v4, v7 bitop3:0x36
	v_or_b32_e32 v7, 0x800, v9
	v_or_b32_e32 v10, 0x1000, v9
	v_or_b32_e32 v11, 0x1800, v9
	s_add_u32 s36, s54, s36
	v_mov_b32_e32 v0, 0
	v_readlane_b32 s45, v253, 2
	v_readlane_b32 s46, v253, 3
	v_readlane_b32 s47, v253, 4
	v_readlane_b32 s48, v253, 5
	v_readlane_b32 s49, v253, 6
	v_readlane_b32 s50, v253, 7
	v_readlane_b32 s51, v253, 8
	s_addc_u32 s37, s34, s37
	s_mov_b32 s38, -2
	s_add_i32 s76, s62, 0xc000
	s_add_i32 s75, s62, 0xe000
	v_add_u32_e32 v138, v5, v1
	v_add_u32_e32 v134, v2, v9
	v_add_u32_e32 v133, v4, v7
	v_add_u32_e32 v132, v4, v10
	v_add_u32_e32 v131, v4, v11
	v_add_u32_e32 v137, v6, v1
	v_add_u32_e32 v136, v8, v1
	v_add_u32_e32 v135, v3, v1
	s_mov_b64 s[6:7], s[50:51]
	v_mov_b32_e32 v1, v0
	v_mov_b32_e32 v2, v0
	v_mov_b32_e32 v3, v0
	v_mov_b32_e32 v4, v0
	v_mov_b32_e32 v5, v0
	v_mov_b32_e32 v6, v0
	v_mov_b32_e32 v7, v0
	v_mov_b32_e32 v8, v0
	v_mov_b32_e32 v9, v0
	v_mov_b32_e32 v10, v0
	v_mov_b32_e32 v11, v0
	v_mov_b32_e32 v12, v0
	v_mov_b32_e32 v13, v0
	v_mov_b32_e32 v14, v0
	v_mov_b32_e32 v15, v0
	v_mov_b32_e32 v16, v0
	v_mov_b32_e32 v17, v0
	v_mov_b32_e32 v18, v0
	v_mov_b32_e32 v19, v0
	v_mov_b32_e32 v20, v0
	v_mov_b32_e32 v21, v0
	v_mov_b32_e32 v22, v0
	v_mov_b32_e32 v23, v0
	v_mov_b32_e32 v24, v0
	v_mov_b32_e32 v25, v0
	v_mov_b32_e32 v26, v0
	v_mov_b32_e32 v27, v0
	v_mov_b32_e32 v28, v0
	v_mov_b32_e32 v29, v0
	v_mov_b32_e32 v30, v0
	v_mov_b32_e32 v31, v0
	v_mov_b32_e32 v32, v0
	v_mov_b32_e32 v33, v0
	v_mov_b32_e32 v34, v0
	v_mov_b32_e32 v35, v0
	v_mov_b32_e32 v36, v0
	v_mov_b32_e32 v37, v0
	v_mov_b32_e32 v38, v0
	v_mov_b32_e32 v39, v0
	v_mov_b32_e32 v40, v0
	v_mov_b32_e32 v41, v0
	v_mov_b32_e32 v42, v0
	v_mov_b32_e32 v43, v0
	v_mov_b32_e32 v44, v0
	v_mov_b32_e32 v45, v0
	v_mov_b32_e32 v46, v0
	v_mov_b32_e32 v47, v0
	v_mov_b32_e32 v48, v0
	v_mov_b32_e32 v49, v0
	v_mov_b32_e32 v50, v0
	v_mov_b32_e32 v51, v0
	v_mov_b32_e32 v52, v0
	v_mov_b32_e32 v53, v0
	v_mov_b32_e32 v54, v0
	v_mov_b32_e32 v55, v0
	v_mov_b32_e32 v56, v0
	v_mov_b32_e32 v57, v0
	v_mov_b32_e32 v58, v0
	v_mov_b32_e32 v59, v0
	v_mov_b32_e32 v60, v0
	v_mov_b32_e32 v61, v0
	v_mov_b32_e32 v62, v0
	v_mov_b32_e32 v63, v0
	v_mov_b32_e32 v64, v0
	v_mov_b32_e32 v65, v0
	v_mov_b32_e32 v66, v0
	v_mov_b32_e32 v67, v0
	v_mov_b32_e32 v68, v0
	v_mov_b32_e32 v69, v0
	v_mov_b32_e32 v70, v0
	v_mov_b32_e32 v71, v0
	v_mov_b32_e32 v72, v0
	v_mov_b32_e32 v73, v0
	v_mov_b32_e32 v74, v0
	v_mov_b32_e32 v75, v0
	v_mov_b32_e32 v76, v0
	v_mov_b32_e32 v77, v0
	v_mov_b32_e32 v78, v0
	v_mov_b32_e32 v79, v0
	v_mov_b32_e32 v80, v0
	v_mov_b32_e32 v81, v0
	v_mov_b32_e32 v82, v0
	v_mov_b32_e32 v83, v0
	v_mov_b32_e32 v84, v0
	v_mov_b32_e32 v85, v0
	v_mov_b32_e32 v86, v0
	v_mov_b32_e32 v87, v0
	v_mov_b32_e32 v88, v0
	v_mov_b32_e32 v89, v0
	v_mov_b32_e32 v90, v0
	v_mov_b32_e32 v91, v0
	v_mov_b32_e32 v92, v0
	v_mov_b32_e32 v93, v0
	v_mov_b32_e32 v94, v0
	v_mov_b32_e32 v95, v0
	v_mov_b32_e32 v96, v0
	v_mov_b32_e32 v97, v0
	v_mov_b32_e32 v98, v0
	v_mov_b32_e32 v99, v0
	v_mov_b32_e32 v100, v0
	v_mov_b32_e32 v101, v0
	v_mov_b32_e32 v102, v0
	v_mov_b32_e32 v103, v0
	v_mov_b32_e32 v104, v0
	v_mov_b32_e32 v105, v0
	v_mov_b32_e32 v106, v0
	v_mov_b32_e32 v107, v0
	v_mov_b32_e32 v108, v0
	v_mov_b32_e32 v109, v0
	v_mov_b32_e32 v110, v0
	v_mov_b32_e32 v111, v0
	v_mov_b32_e32 v112, v0
	v_mov_b32_e32 v113, v0
	v_mov_b32_e32 v114, v0
	v_mov_b32_e32 v115, v0
	v_mov_b32_e32 v116, v0
	v_mov_b32_e32 v117, v0
	v_mov_b32_e32 v118, v0
	v_mov_b32_e32 v119, v0
	v_mov_b32_e32 v120, v0
	v_mov_b32_e32 v121, v0
	v_mov_b32_e32 v122, v0
	v_mov_b32_e32 v123, v0
	v_mov_b32_e32 v124, v0
	v_mov_b32_e32 v125, v0
	v_mov_b32_e32 v126, v0
	v_mov_b32_e32 v127, v0
	s_mov_b64 s[44:45], 0x20560080
	s_mov_b64 s[46:47], 0xd400100
	s_mov_b64 s[48:49], 0x20400100
	s_mov_b64 s[50:51], 0xd560100
	s_mov_b64 s[90:91], 0x20560100
	s_mov_b64 s[92:93], 0xd400180
	s_mov_b64 s[96:97], 0x20400180
	s_mov_b64 vcc, 0xd560180
	s_barrier
	.p2align	6

.Lhf_191:
	s_lshl_b64 s[36:37], s[6:7], 12
	s_add_u32 s4, s67, s36
	s_addc_u32 s5, s60, s37
	v_mov_b32_e32 v2, v130
	v_mov_b32_e32 v196, v128
	s_barrier
	s_add_i32 s7, s52, 0x18000
	v_lshl_add_u64 v[4:5], s[4:5], 0, v[196:197]
	v_mov_b32_e32 v3, v197
	v_lshl_add_u64 v[4:5], v[4:5], 0, s[94:95]
	s_mov_b32 m0, s7
	v_lshl_add_u64 v[2:3], s[4:5], 0, v[2:3]
	s_add_i32 s53, s52, 0x1a000
	s_lshl_b64 s[4:5], s[8:9], 12
	v_readlane_b32 s38, v254, 12
	global_load_lds_dwordx4 v[4:5], off
	v_lshl_add_u64 v[2:3], v[2:3], 0, s[94:95]
	s_mov_b32 m0, s53
	v_readlane_b32 s39, v254, 13
	s_add_u32 s38, s38, s4
	global_load_lds_dwordx4 v[2:3], off
	s_addc_u32 s39, s39, s5
	v_mov_b32_e32 v2, v130
	v_mov_b32_e32 v196, v128
	s_add_i32 s9, s52, 0x8000
	v_lshl_add_u64 v[4:5], s[38:39], 0, v[196:197]
	v_mov_b32_e32 v3, v197
	v_lshl_add_u64 v[4:5], v[4:5], 0, s[94:95]
	s_mov_b32 m0, s9
	v_lshl_add_u64 v[2:3], s[38:39], 0, v[2:3]
	s_add_i32 s33, s52, 0xa000
	s_lshl_b64 s[28:29], s[28:29], 12
	global_load_lds_dwordx4 v[4:5], off
	v_lshl_add_u64 v[2:3], v[2:3], 0, s[94:95]
	s_mov_b32 m0, s33
	s_add_u32 s28, s67, s28
	global_load_lds_dwordx4 v[2:3], off
	s_addc_u32 s29, s60, s29
	v_mov_b32_e32 v2, v130
	v_mov_b32_e32 v196, v128
	s_add_i32 s65, s52, 0x1c000
	v_lshl_add_u64 v[4:5], s[28:29], 0, v[196:197]
	v_mov_b32_e32 v3, v197
	v_lshl_add_u64 v[4:5], v[4:5], 0, s[94:95]
	s_mov_b32 m0, s65
	v_lshl_add_u64 v[2:3], s[28:29], 0, v[2:3]
	s_add_i32 s66, s52, 0x1e000
	global_load_lds_dwordx4 v[4:5], off
	v_lshl_add_u64 v[2:3], v[2:3], 0, s[94:95]
	s_mov_b32 m0, s66
	v_and_b32_e32 v6, 15, v132
	global_load_lds_dwordx4 v[2:3], off
	v_lshlrev_b32_e32 v0, 12, v0
	v_and_b32_e32 v7, 48, v132
	v_and_b32_e32 v2, 0x3000, v0
	v_lshlrev_b32_e32 v0, 6, v6
	v_lshlrev_b32_e32 v4, 2, v132
	v_or_b32_e32 v3, v0, v7
	v_and_b32_e32 v4, 32, v4
	s_mov_b32 s28, 0x10000
	v_bitop3_b32 v5, v0, v4, v7 bitop3:0x36
	v_bitop3_b32 v6, v3, s28, v4 bitop3:0xde
	s_mov_b32 s28, 0x14000
	v_lshlrev_b32_e32 v0, 6, v132
	s_waitcnt vmcnt(6)
	v_bitop3_b32 v8, v3, s28, v4 bitop3:0xde
	s_mov_b32 s28, 0x1c000
	v_lshlrev_b32_e32 v1, 13, v1
	v_and_b32_e32 v0, 0x3c0, v0
	v_readlane_b32 s44, v253, 1
	v_bitop3_b32 v9, v3, s2, v4 bitop3:0xde
	v_bitop3_b32 v3, v3, s28, v4 bitop3:0xde
	v_bitop3_b32 v4, v0, v4, v7 bitop3:0x36
	v_or_b32_e32 v7, 0x800, v1
	v_or_b32_e32 v10, 0x1000, v1
	v_or_b32_e32 v11, 0x1800, v1
	s_add_u32 s36, s41, s36
	v_mov_b32_e32 v0, 0
	v_readlane_b32 s45, v253, 2
	v_readlane_b32 s46, v253, 3
	v_readlane_b32 s47, v253, 4
	v_readlane_b32 s48, v253, 5
	v_readlane_b32 s49, v253, 6
	v_readlane_b32 s50, v253, 7
	v_readlane_b32 s51, v253, 8
	s_addc_u32 s37, s34, s37
	s_mov_b32 s38, -2
	v_add_u32_e32 v129, v6, v2
	v_add_u32_e32 v136, v5, v1
	v_add_u32_e32 v135, v4, v7
	v_add_u32_e32 v134, v4, v10
	v_add_u32_e32 v133, v4, v11
	v_add_u32_e32 v139, v8, v2
	v_add_u32_e32 v138, v9, v2
	v_add_u32_e32 v137, v3, v2
	s_mov_b64 s[56:57], s[50:51]
	v_mov_b32_e32 v1, v0
	v_mov_b32_e32 v2, v0
	v_mov_b32_e32 v3, v0
	v_mov_b32_e32 v4, v0
	v_mov_b32_e32 v5, v0
	v_mov_b32_e32 v6, v0
	v_mov_b32_e32 v7, v0
	v_mov_b32_e32 v8, v0
	v_mov_b32_e32 v9, v0
	v_mov_b32_e32 v10, v0
	v_mov_b32_e32 v11, v0
	v_mov_b32_e32 v12, v0
	v_mov_b32_e32 v13, v0
	v_mov_b32_e32 v14, v0
	v_mov_b32_e32 v15, v0
	v_mov_b32_e32 v16, v0
	v_mov_b32_e32 v17, v0
	v_mov_b32_e32 v18, v0
	v_mov_b32_e32 v19, v0
	v_mov_b32_e32 v20, v0
	v_mov_b32_e32 v21, v0
	v_mov_b32_e32 v22, v0
	v_mov_b32_e32 v23, v0
	v_mov_b32_e32 v24, v0
	v_mov_b32_e32 v25, v0
	v_mov_b32_e32 v26, v0
	v_mov_b32_e32 v27, v0
	v_mov_b32_e32 v28, v0
	v_mov_b32_e32 v29, v0
	v_mov_b32_e32 v30, v0
	v_mov_b32_e32 v31, v0
	v_mov_b32_e32 v32, v0
	v_mov_b32_e32 v33, v0
	v_mov_b32_e32 v34, v0
	v_mov_b32_e32 v35, v0
	v_mov_b32_e32 v36, v0
	v_mov_b32_e32 v37, v0
	v_mov_b32_e32 v38, v0
	v_mov_b32_e32 v39, v0
	v_mov_b32_e32 v40, v0
	v_mov_b32_e32 v41, v0
	v_mov_b32_e32 v42, v0
	v_mov_b32_e32 v43, v0
	v_mov_b32_e32 v44, v0
	v_mov_b32_e32 v45, v0
	v_mov_b32_e32 v46, v0
	v_mov_b32_e32 v47, v0
	v_mov_b32_e32 v48, v0
	v_mov_b32_e32 v49, v0
	v_mov_b32_e32 v50, v0
	v_mov_b32_e32 v51, v0
	v_mov_b32_e32 v52, v0
	v_mov_b32_e32 v53, v0
	v_mov_b32_e32 v54, v0
	v_mov_b32_e32 v55, v0
	v_mov_b32_e32 v56, v0
	v_mov_b32_e32 v57, v0
	v_mov_b32_e32 v58, v0
	v_mov_b32_e32 v59, v0
	v_mov_b32_e32 v60, v0
	v_mov_b32_e32 v61, v0
	v_mov_b32_e32 v62, v0
	v_mov_b32_e32 v63, v0
	v_mov_b32_e32 v64, v0
	v_mov_b32_e32 v65, v0
	v_mov_b32_e32 v66, v0
	v_mov_b32_e32 v67, v0
	v_mov_b32_e32 v68, v0
	v_mov_b32_e32 v69, v0
	v_mov_b32_e32 v70, v0
	v_mov_b32_e32 v71, v0
	v_mov_b32_e32 v72, v0
	v_mov_b32_e32 v73, v0
	v_mov_b32_e32 v74, v0
	v_mov_b32_e32 v75, v0
	v_mov_b32_e32 v76, v0
	v_mov_b32_e32 v77, v0
	v_mov_b32_e32 v78, v0
	v_mov_b32_e32 v79, v0
	v_mov_b32_e32 v80, v0
	v_mov_b32_e32 v81, v0
	v_mov_b32_e32 v82, v0
	v_mov_b32_e32 v83, v0
	v_mov_b32_e32 v84, v0
	v_mov_b32_e32 v85, v0
	v_mov_b32_e32 v86, v0
	v_mov_b32_e32 v87, v0
	v_mov_b32_e32 v88, v0
	v_mov_b32_e32 v89, v0
	v_mov_b32_e32 v90, v0
	v_mov_b32_e32 v91, v0
	v_mov_b32_e32 v92, v0
	v_mov_b32_e32 v93, v0
	v_mov_b32_e32 v94, v0
	v_mov_b32_e32 v95, v0
	v_mov_b32_e32 v96, v0
	v_mov_b32_e32 v97, v0
	v_mov_b32_e32 v98, v0
	v_mov_b32_e32 v99, v0
	v_mov_b32_e32 v100, v0
	v_mov_b32_e32 v101, v0
	v_mov_b32_e32 v102, v0
	v_mov_b32_e32 v103, v0
	v_mov_b32_e32 v104, v0
	v_mov_b32_e32 v105, v0
	v_mov_b32_e32 v106, v0
	v_mov_b32_e32 v107, v0
	v_mov_b32_e32 v108, v0
	v_mov_b32_e32 v109, v0
	v_mov_b32_e32 v110, v0
	v_mov_b32_e32 v111, v0
	v_mov_b32_e32 v112, v0
	v_mov_b32_e32 v113, v0
	v_mov_b32_e32 v114, v0
	v_mov_b32_e32 v115, v0
	v_mov_b32_e32 v116, v0
	v_mov_b32_e32 v117, v0
	v_mov_b32_e32 v118, v0
	v_mov_b32_e32 v119, v0
	v_mov_b32_e32 v120, v0
	v_mov_b32_e32 v121, v0
	v_mov_b32_e32 v122, v0
	v_mov_b32_e32 v123, v0
	v_mov_b32_e32 v124, v0
	v_mov_b32_e32 v125, v0
	v_mov_b32_e32 v126, v0
	v_mov_b32_e32 v127, v0
	s_mov_b64 s[44:45], 0x16080080
	s_mov_b64 s[46:47], 0x7c00100
	s_mov_b64 s[48:49], 0x16000100
	s_mov_b64 s[50:51], 0x7c80100
	s_mov_b64 s[54:55], 0x16080100
	s_mov_b64 s[68:69], 0x7c00180
	s_mov_b64 s[70:71], 0x16000180
	s_mov_b64 s[72:73], 0x7c80180
	s_barrier
	.p2align	6

.Lh1_137:
	s_or_b64 exec, exec, s[66:67]
	v_mov_b32_e32 v196, v128
	v_mov_b32_e32 v2, v130
	s_waitcnt vmcnt(2)
	s_barrier
	s_add_i32 s66, s53, 0x18000
	v_lshl_add_u64 v[4:5], s[64:65], 0, v[196:197]
	v_mov_b32_e32 v3, v197
	v_lshl_add_u64 v[4:5], v[4:5], 0, s[94:95]
	s_mov_b32 m0, s66
	v_lshl_add_u64 v[2:3], s[64:65], 0, v[2:3]
	s_add_i32 s64, s53, 0x1a000
	global_load_lds_dwordx4 v[4:5], off
	v_lshl_add_u64 v[2:3], v[2:3], 0, s[94:95]
	s_mov_b32 m0, s64
	v_mov_b32_e32 v196, v128
	global_load_lds_dwordx4 v[2:3], off
	v_mov_b32_e32 v2, v130
	s_add_i32 s65, s53, 0x8000
	v_lshl_add_u64 v[4:5], s[62:63], 0, v[196:197]
	v_mov_b32_e32 v3, v197
	v_lshl_add_u64 v[4:5], v[4:5], 0, s[94:95]
	s_mov_b32 m0, s65
	v_lshl_add_u64 v[2:3], s[62:63], 0, v[2:3]
	s_add_i32 s67, s53, 0xa000
	global_load_lds_dwordx4 v[4:5], off
	v_lshl_add_u64 v[2:3], v[2:3], 0, s[94:95]
	s_mov_b32 m0, s67
	v_mov_b32_e32 v196, v128
	global_load_lds_dwordx4 v[2:3], off
	v_mov_b32_e32 v2, v130
	s_add_i32 s33, s53, 0x1c000
	v_lshl_add_u64 v[4:5], s[60:61], 0, v[196:197]
	v_mov_b32_e32 v3, v197
	v_lshl_add_u64 v[4:5], v[4:5], 0, s[94:95]
	s_mov_b32 m0, s33
	v_lshl_add_u64 v[2:3], s[60:61], 0, v[2:3]
	s_add_i32 s73, s53, 0x1e000
	global_load_lds_dwordx4 v[4:5], off
	v_lshl_add_u64 v[2:3], v[2:3], 0, s[94:95]
	s_mov_b32 m0, s73
	v_and_b32_e32 v6, 15, v132
	global_load_lds_dwordx4 v[2:3], off
	v_and_b32_e32 v7, 48, v132
	v_lshlrev_b32_e32 v2, 6, v6
	v_lshlrev_b32_e32 v4, 2, v132
	v_or_b32_e32 v3, v2, v7
	v_and_b32_e32 v4, 32, v4
	s_mov_b32 s36, 0x10000
	v_bitop3_b32 v5, v3, s36, v4 bitop3:0xde
	s_mov_b32 s36, 0x14000
	v_lshlrev_b32_e32 v9, 13, v0
	v_lshlrev_b32_e32 v0, 6, v132
	s_waitcnt vmcnt(6)
	v_lshlrev_b32_e32 v1, 12, v1
	v_bitop3_b32 v6, v3, s36, v4 bitop3:0xde
	s_mov_b32 s36, 0x1c000
	v_and_b32_e32 v0, 0x3c0, v0
	v_readlane_b32 s44, v253, 1
	v_and_b32_e32 v1, 0x3000, v1
	v_bitop3_b32 v2, v2, v4, v7 bitop3:0x36
	v_bitop3_b32 v8, v3, s2, v4 bitop3:0xde
	v_bitop3_b32 v3, v3, s36, v4 bitop3:0xde
	v_bitop3_b32 v4, v0, v4, v7 bitop3:0x36
	v_or_b32_e32 v7, 0x800, v9
	v_or_b32_e32 v10, 0x1000, v9
	v_or_b32_e32 v11, 0x1800, v9
	s_add_u32 s36, s4, s28
	v_mov_b32_e32 v0, 0
	v_readlane_b32 s45, v253, 2
	v_readlane_b32 s46, v253, 3
	v_readlane_b32 s47, v253, 4
	v_readlane_b32 s48, v253, 5
	v_readlane_b32 s49, v253, 6
	v_readlane_b32 s50, v253, 7
	v_readlane_b32 s51, v253, 8
	s_addc_u32 s37, s5, s29
	s_mov_b32 s38, -2
	v_add_u32_e32 v129, v5, v1
	v_add_u32_e32 v136, v2, v9
	v_add_u32_e32 v135, v4, v7
	v_add_u32_e32 v134, v4, v10
	v_add_u32_e32 v133, v4, v11
	v_add_u32_e32 v139, v6, v1
	v_add_u32_e32 v138, v8, v1
	v_add_u32_e32 v137, v3, v1
	s_mov_b64 s[60:61], s[50:51]
	v_mov_b32_e32 v1, v0
	v_mov_b32_e32 v2, v0
	v_mov_b32_e32 v3, v0
	v_mov_b32_e32 v4, v0
	v_mov_b32_e32 v5, v0
	v_mov_b32_e32 v6, v0
	v_mov_b32_e32 v7, v0
	v_mov_b32_e32 v8, v0
	v_mov_b32_e32 v9, v0
	v_mov_b32_e32 v10, v0
	v_mov_b32_e32 v11, v0
	v_mov_b32_e32 v12, v0
	v_mov_b32_e32 v13, v0
	v_mov_b32_e32 v14, v0
	v_mov_b32_e32 v15, v0
	v_mov_b32_e32 v16, v0
	v_mov_b32_e32 v17, v0
	v_mov_b32_e32 v18, v0
	v_mov_b32_e32 v19, v0
	v_mov_b32_e32 v20, v0
	v_mov_b32_e32 v21, v0
	v_mov_b32_e32 v22, v0
	v_mov_b32_e32 v23, v0
	v_mov_b32_e32 v24, v0
	v_mov_b32_e32 v25, v0
	v_mov_b32_e32 v26, v0
	v_mov_b32_e32 v27, v0
	v_mov_b32_e32 v28, v0
	v_mov_b32_e32 v29, v0
	v_mov_b32_e32 v30, v0
	v_mov_b32_e32 v31, v0
	v_mov_b32_e32 v32, v0
	v_mov_b32_e32 v33, v0
	v_mov_b32_e32 v34, v0
	v_mov_b32_e32 v35, v0
	v_mov_b32_e32 v36, v0
	v_mov_b32_e32 v37, v0
	v_mov_b32_e32 v38, v0
	v_mov_b32_e32 v39, v0
	v_mov_b32_e32 v40, v0
	v_mov_b32_e32 v41, v0
	v_mov_b32_e32 v42, v0
	v_mov_b32_e32 v43, v0
	v_mov_b32_e32 v44, v0
	v_mov_b32_e32 v45, v0
	v_mov_b32_e32 v46, v0
	v_mov_b32_e32 v47, v0
	v_mov_b32_e32 v48, v0
	v_mov_b32_e32 v49, v0
	v_mov_b32_e32 v50, v0
	v_mov_b32_e32 v51, v0
	v_mov_b32_e32 v52, v0
	v_mov_b32_e32 v53, v0
	v_mov_b32_e32 v54, v0
	v_mov_b32_e32 v55, v0
	v_mov_b32_e32 v56, v0
	v_mov_b32_e32 v57, v0
	v_mov_b32_e32 v58, v0
	v_mov_b32_e32 v59, v0
	v_mov_b32_e32 v60, v0
	v_mov_b32_e32 v61, v0
	v_mov_b32_e32 v62, v0
	v_mov_b32_e32 v63, v0
	v_mov_b32_e32 v64, v0
	v_mov_b32_e32 v65, v0
	v_mov_b32_e32 v66, v0
	v_mov_b32_e32 v67, v0
	v_mov_b32_e32 v68, v0
	v_mov_b32_e32 v69, v0
	v_mov_b32_e32 v70, v0
	v_mov_b32_e32 v71, v0
	v_mov_b32_e32 v72, v0
	v_mov_b32_e32 v73, v0
	v_mov_b32_e32 v74, v0
	v_mov_b32_e32 v75, v0
	v_mov_b32_e32 v76, v0
	v_mov_b32_e32 v77, v0
	v_mov_b32_e32 v78, v0
	v_mov_b32_e32 v79, v0
	v_mov_b32_e32 v80, v0
	v_mov_b32_e32 v81, v0
	v_mov_b32_e32 v82, v0
	v_mov_b32_e32 v83, v0
	v_mov_b32_e32 v84, v0
	v_mov_b32_e32 v85, v0
	v_mov_b32_e32 v86, v0
	v_mov_b32_e32 v87, v0
	v_mov_b32_e32 v88, v0
	v_mov_b32_e32 v89, v0
	v_mov_b32_e32 v90, v0
	v_mov_b32_e32 v91, v0
	v_mov_b32_e32 v92, v0
	v_mov_b32_e32 v93, v0
	v_mov_b32_e32 v94, v0
	v_mov_b32_e32 v95, v0
	v_mov_b32_e32 v96, v0
	v_mov_b32_e32 v97, v0
	v_mov_b32_e32 v98, v0
	v_mov_b32_e32 v99, v0
	v_mov_b32_e32 v100, v0
	v_mov_b32_e32 v101, v0
	v_mov_b32_e32 v102, v0
	v_mov_b32_e32 v103, v0
	v_mov_b32_e32 v104, v0
	v_mov_b32_e32 v105, v0
	v_mov_b32_e32 v106, v0
	v_mov_b32_e32 v107, v0
	v_mov_b32_e32 v108, v0
	v_mov_b32_e32 v109, v0
	v_mov_b32_e32 v110, v0
	v_mov_b32_e32 v111, v0
	v_mov_b32_e32 v112, v0
	v_mov_b32_e32 v113, v0
	v_mov_b32_e32 v114, v0
	v_mov_b32_e32 v115, v0
	v_mov_b32_e32 v116, v0
	v_mov_b32_e32 v117, v0
	v_mov_b32_e32 v118, v0
	v_mov_b32_e32 v119, v0
	v_mov_b32_e32 v120, v0
	v_mov_b32_e32 v121, v0
	v_mov_b32_e32 v122, v0
	v_mov_b32_e32 v123, v0
	v_mov_b32_e32 v124, v0
	v_mov_b32_e32 v125, v0
	v_mov_b32_e32 v126, v0
	v_mov_b32_e32 v127, v0
	s_mov_b64 s[44:45], 0x2c480080
	s_mov_b64 s[46:47], 0x6c00100
	s_mov_b64 s[48:49], 0x2c400100
	s_mov_b64 s[50:51], 0x6c80100
	s_mov_b64 s[74:75], 0x2c480100
	s_mov_b64 s[90:91], 0x6c00180
	s_mov_b64 s[92:93], 0x2c400180
	s_mov_b64 s[96:97], 0x6c80180
	s_barrier
	.p2align	6

.LBB0_254:
	s_or_b64 exec, exec, s[66:67]
	v_mov_b32_e32 v196, v128
	v_mov_b32_e32 v2, v130
	s_waitcnt vmcnt(4)
	s_barrier
	s_add_i32 s66, s53, 0x18000
	v_lshl_add_u64 v[4:5], s[64:65], 0, v[196:197]
	v_mov_b32_e32 v3, v197
	v_lshl_add_u64 v[4:5], v[4:5], 0, s[94:95]
	s_mov_b32 m0, s66
	v_lshl_add_u64 v[2:3], s[64:65], 0, v[2:3]
	s_add_i32 s64, s53, 0x1a000
	global_load_lds_dwordx4 v[4:5], off
	v_lshl_add_u64 v[2:3], v[2:3], 0, s[94:95]
	s_mov_b32 m0, s64
	v_mov_b32_e32 v196, v128
	global_load_lds_dwordx4 v[2:3], off
	v_mov_b32_e32 v2, v130
	s_add_i32 s65, s53, 0x8000
	v_lshl_add_u64 v[4:5], s[62:63], 0, v[196:197]
	v_mov_b32_e32 v3, v197
	v_lshl_add_u64 v[4:5], v[4:5], 0, s[94:95]
	s_mov_b32 m0, s65
	v_lshl_add_u64 v[2:3], s[62:63], 0, v[2:3]
	s_add_i32 s67, s53, 0xa000
	global_load_lds_dwordx4 v[4:5], off
	v_lshl_add_u64 v[2:3], v[2:3], 0, s[94:95]
	s_mov_b32 m0, s67
	v_mov_b32_e32 v196, v128
	global_load_lds_dwordx4 v[2:3], off
	v_mov_b32_e32 v2, v130
	s_add_i32 s33, s53, 0x1c000
	v_lshl_add_u64 v[4:5], s[60:61], 0, v[196:197]
	v_mov_b32_e32 v3, v197
	v_lshl_add_u64 v[4:5], v[4:5], 0, s[94:95]
	s_mov_b32 m0, s33
	v_lshl_add_u64 v[2:3], s[60:61], 0, v[2:3]
	s_add_i32 s73, s53, 0x1e000
	global_load_lds_dwordx4 v[4:5], off
	v_lshl_add_u64 v[2:3], v[2:3], 0, s[94:95]
	s_mov_b32 m0, s73
	v_and_b32_e32 v6, 15, v132
	global_load_lds_dwordx4 v[2:3], off
	v_and_b32_e32 v7, 48, v132
	v_lshlrev_b32_e32 v2, 6, v6
	v_lshlrev_b32_e32 v4, 2, v132
	v_or_b32_e32 v3, v2, v7
	v_and_b32_e32 v4, 32, v4
	s_mov_b32 s36, 0x10000
	v_bitop3_b32 v5, v3, s36, v4 bitop3:0xde
	s_mov_b32 s36, 0x14000
	v_lshlrev_b32_e32 v9, 13, v0
	v_lshlrev_b32_e32 v0, 6, v132
	s_waitcnt vmcnt(6)
	v_lshlrev_b32_e32 v1, 12, v1
	v_bitop3_b32 v6, v3, s36, v4 bitop3:0xde
	s_mov_b32 s36, 0x1c000
	v_and_b32_e32 v0, 0x3c0, v0
	v_readlane_b32 s44, v253, 1
	v_and_b32_e32 v1, 0x3000, v1
	v_bitop3_b32 v2, v2, v4, v7 bitop3:0x36
	v_bitop3_b32 v8, v3, s2, v4 bitop3:0xde
	v_bitop3_b32 v3, v3, s36, v4 bitop3:0xde
	v_bitop3_b32 v4, v0, v4, v7 bitop3:0x36
	v_or_b32_e32 v7, 0x800, v9
	v_or_b32_e32 v10, 0x1000, v9
	v_or_b32_e32 v11, 0x1800, v9
	s_add_u32 s36, s4, s28
	v_mov_b32_e32 v0, 0
	v_readlane_b32 s45, v253, 2
	v_readlane_b32 s46, v253, 3
	v_readlane_b32 s47, v253, 4
	v_readlane_b32 s48, v253, 5
	v_readlane_b32 s49, v253, 6
	v_readlane_b32 s50, v253, 7
	v_readlane_b32 s51, v253, 8
	s_addc_u32 s37, s5, s29
	s_mov_b32 s38, -2
	v_add_u32_e32 v129, v5, v1
	v_add_u32_e32 v136, v2, v9
	v_add_u32_e32 v135, v4, v7
	v_add_u32_e32 v134, v4, v10
	v_add_u32_e32 v133, v4, v11
	v_add_u32_e32 v139, v6, v1
	v_add_u32_e32 v138, v8, v1
	v_add_u32_e32 v137, v3, v1
	s_mov_b64 s[60:61], s[50:51]
	v_mov_b32_e32 v1, v0
	v_mov_b32_e32 v2, v0
	v_mov_b32_e32 v3, v0
	v_mov_b32_e32 v4, v0
	v_mov_b32_e32 v5, v0
	v_mov_b32_e32 v6, v0
	v_mov_b32_e32 v7, v0
	v_mov_b32_e32 v8, v0
	v_mov_b32_e32 v9, v0
	v_mov_b32_e32 v10, v0
	v_mov_b32_e32 v11, v0
	v_mov_b32_e32 v12, v0
	v_mov_b32_e32 v13, v0
	v_mov_b32_e32 v14, v0
	v_mov_b32_e32 v15, v0
	v_mov_b32_e32 v16, v0
	v_mov_b32_e32 v17, v0
	v_mov_b32_e32 v18, v0
	v_mov_b32_e32 v19, v0
	v_mov_b32_e32 v20, v0
	v_mov_b32_e32 v21, v0
	v_mov_b32_e32 v22, v0
	v_mov_b32_e32 v23, v0
	v_mov_b32_e32 v24, v0
	v_mov_b32_e32 v25, v0
	v_mov_b32_e32 v26, v0
	v_mov_b32_e32 v27, v0
	v_mov_b32_e32 v28, v0
	v_mov_b32_e32 v29, v0
	v_mov_b32_e32 v30, v0
	v_mov_b32_e32 v31, v0
	v_mov_b32_e32 v32, v0
	v_mov_b32_e32 v33, v0
	v_mov_b32_e32 v34, v0
	v_mov_b32_e32 v35, v0
	v_mov_b32_e32 v36, v0
	v_mov_b32_e32 v37, v0
	v_mov_b32_e32 v38, v0
	v_mov_b32_e32 v39, v0
	v_mov_b32_e32 v40, v0
	v_mov_b32_e32 v41, v0
	v_mov_b32_e32 v42, v0
	v_mov_b32_e32 v43, v0
	v_mov_b32_e32 v44, v0
	v_mov_b32_e32 v45, v0
	v_mov_b32_e32 v46, v0
	v_mov_b32_e32 v47, v0
	v_mov_b32_e32 v48, v0
	v_mov_b32_e32 v49, v0
	v_mov_b32_e32 v50, v0
	v_mov_b32_e32 v51, v0
	v_mov_b32_e32 v52, v0
	v_mov_b32_e32 v53, v0
	v_mov_b32_e32 v54, v0
	v_mov_b32_e32 v55, v0
	v_mov_b32_e32 v56, v0
	v_mov_b32_e32 v57, v0
	v_mov_b32_e32 v58, v0
	v_mov_b32_e32 v59, v0
	v_mov_b32_e32 v60, v0
	v_mov_b32_e32 v61, v0
	v_mov_b32_e32 v62, v0
	v_mov_b32_e32 v63, v0
	v_mov_b32_e32 v64, v0
	v_mov_b32_e32 v65, v0
	v_mov_b32_e32 v66, v0
	v_mov_b32_e32 v67, v0
	v_mov_b32_e32 v68, v0
	v_mov_b32_e32 v69, v0
	v_mov_b32_e32 v70, v0
	v_mov_b32_e32 v71, v0
	v_mov_b32_e32 v72, v0
	v_mov_b32_e32 v73, v0
	v_mov_b32_e32 v74, v0
	v_mov_b32_e32 v75, v0
	v_mov_b32_e32 v76, v0
	v_mov_b32_e32 v77, v0
	v_mov_b32_e32 v78, v0
	v_mov_b32_e32 v79, v0
	v_mov_b32_e32 v80, v0
	v_mov_b32_e32 v81, v0
	v_mov_b32_e32 v82, v0
	v_mov_b32_e32 v83, v0
	v_mov_b32_e32 v84, v0
	v_mov_b32_e32 v85, v0
	v_mov_b32_e32 v86, v0
	v_mov_b32_e32 v87, v0
	v_mov_b32_e32 v88, v0
	v_mov_b32_e32 v89, v0
	v_mov_b32_e32 v90, v0
	v_mov_b32_e32 v91, v0
	v_mov_b32_e32 v92, v0
	v_mov_b32_e32 v93, v0
	v_mov_b32_e32 v94, v0
	v_mov_b32_e32 v95, v0
	v_mov_b32_e32 v96, v0
	v_mov_b32_e32 v97, v0
	v_mov_b32_e32 v98, v0
	v_mov_b32_e32 v99, v0
	v_mov_b32_e32 v100, v0
	v_mov_b32_e32 v101, v0
	v_mov_b32_e32 v102, v0
	v_mov_b32_e32 v103, v0
	v_mov_b32_e32 v104, v0
	v_mov_b32_e32 v105, v0
	v_mov_b32_e32 v106, v0
	v_mov_b32_e32 v107, v0
	v_mov_b32_e32 v108, v0
	v_mov_b32_e32 v109, v0
	v_mov_b32_e32 v110, v0
	v_mov_b32_e32 v111, v0
	v_mov_b32_e32 v112, v0
	v_mov_b32_e32 v113, v0
	v_mov_b32_e32 v114, v0
	v_mov_b32_e32 v115, v0
	v_mov_b32_e32 v116, v0
	v_mov_b32_e32 v117, v0
	v_mov_b32_e32 v118, v0
	v_mov_b32_e32 v119, v0
	v_mov_b32_e32 v120, v0
	v_mov_b32_e32 v121, v0
	v_mov_b32_e32 v122, v0
	v_mov_b32_e32 v123, v0
	v_mov_b32_e32 v124, v0
	v_mov_b32_e32 v125, v0
	v_mov_b32_e32 v126, v0
	v_mov_b32_e32 v127, v0
	s_mov_b64 s[44:45], 0x2c480080
	s_mov_b64 s[46:47], 0x6c00100
	s_mov_b64 s[48:49], 0x2c400100
	s_mov_b64 s[50:51], 0x6c80100
	s_mov_b64 s[74:75], 0x2c480100
	s_mov_b64 s[90:91], 0x6c00180
	s_mov_b64 s[92:93], 0x2c400180
	s_mov_b64 s[96:97], 0x6c80180
	s_barrier
	.p2align	6

.LBB0_313:
	s_or_b64 exec, exec, s[96:97]
	v_mov_b32_e32 v196, v160
	v_mov_b32_e32 v166, v161
	s_waitcnt vmcnt(4)
	s_barrier
	s_add_i32 s70, s34, 0x18000
	v_lshl_add_u64 v[168:169], s[6:7], 0, v[196:197]
	v_mov_b32_e32 v167, v197
	v_lshl_add_u64 v[168:169], v[168:169], 0, s[94:95]
	s_mov_b32 m0, s70
	v_lshl_add_u64 v[166:167], s[6:7], 0, v[166:167]
	s_add_i32 s71, s34, 0x1a000
	global_load_lds_dwordx4 v[168:169], off
	v_lshl_add_u64 v[166:167], v[166:167], 0, s[94:95]
	s_mov_b32 m0, s71
	v_mov_b32_e32 v196, v160
	global_load_lds_dwordx4 v[166:167], off
	v_mov_b32_e32 v166, v161
	s_add_i32 s72, s34, 0x8000
	v_lshl_add_u64 v[168:169], s[90:91], 0, v[196:197]
	v_mov_b32_e32 v167, v197
	v_lshl_add_u64 v[168:169], v[168:169], 0, s[94:95]
	s_mov_b32 m0, s72
	v_lshl_add_u64 v[166:167], s[90:91], 0, v[166:167]
	s_add_i32 s73, s34, 0xa000
	global_load_lds_dwordx4 v[168:169], off
	v_lshl_add_u64 v[166:167], v[166:167], 0, s[94:95]
	s_mov_b32 m0, s73
	v_mov_b32_e32 v196, v160
	global_load_lds_dwordx4 v[166:167], off
	v_mov_b32_e32 v166, v161
	s_add_i32 s75, s34, 0x1c000
	v_lshl_add_u64 v[168:169], s[92:93], 0, v[196:197]
	v_mov_b32_e32 v167, v197
	v_lshl_add_u64 v[168:169], v[168:169], 0, s[94:95]
	s_mov_b32 m0, s75
	v_lshl_add_u64 v[166:167], s[92:93], 0, v[166:167]
	s_add_i32 s89, s34, 0x1e000
	global_load_lds_dwordx4 v[168:169], off
	v_lshl_add_u64 v[166:167], v[166:167], 0, s[94:95]
	s_mov_b32 m0, s89
	v_and_b32_e32 v165, 15, v164
	global_load_lds_dwordx4 v[166:167], off
	v_lshlrev_b32_e32 v162, 12, v162
	v_and_b32_e32 v166, 48, v164
	v_and_b32_e32 v167, 0x3000, v162
	v_lshlrev_b32_e32 v162, 6, v165
	v_lshlrev_b32_e32 v168, 2, v164
	v_or_b32_e32 v165, v162, v166
	v_and_b32_e32 v168, 32, v168
	s_mov_b32 s36, 0x10000
	v_bitop3_b32 v169, v165, s36, v168 bitop3:0xde
	s_mov_b32 s36, 0x14000
	v_bitop3_b32 v171, v165, s36, v168 bitop3:0xde
	s_mov_b32 s36, 0x1c000
	s_lshr_b32 s33, s37, 6
	v_bitop3_b32 v173, v165, s36, v168 bitop3:0xde
	s_mul_i32 s36, s63, s37
	s_mul_hi_u32 s38, s62, s37
	s_add_i32 s74, s33, -2
	s_add_i32 s38, s38, s36
	s_mul_i32 s36, s62, s37
	s_add_u32 s82, s8, s36
	v_bitop3_b32 v172, v165, s2, v168 bitop3:0xde
	v_lshlrev_b32_e32 v165, 6, v164
	s_addc_u32 s36, s9, s38
	s_mul_i32 s8, s77, s37
	s_mul_hi_u32 s9, s76, s37
	s_waitcnt vmcnt(6)
	v_lshlrev_b32_e32 v163, 13, v163
	v_and_b32_e32 v165, 0x3c0, v165
	s_add_i32 s9, s9, s8
	s_mul_i32 s8, s76, s37
	v_bitop3_b32 v162, v162, v168, v166 bitop3:0x36
	v_bitop3_b32 v168, v165, v168, v166 bitop3:0x36
	v_or_b32_e32 v165, 0x800, v163
	v_or_b32_e32 v174, 0x1000, v163
	v_or_b32_e32 v175, 0x1800, v163
	s_add_u32 s37, s28, s8
	s_addc_u32 s38, s29, s9
	s_mov_b32 s39, 0
	s_mov_b64 vcc, 0
	v_add_u32_e32 v170, v169, v167
	v_add_u32_e32 v166, v162, v163
	v_add_u32_e32 v165, v168, v165
	v_add_u32_e32 v163, v168, v174
	v_add_u32_e32 v162, v168, v175
	v_add_u32_e32 v169, v171, v167
	v_add_u32_e32 v168, v172, v167
	v_add_u32_e32 v167, v173, v167
	s_barrier
	.p2align	6

.LBB0_567:
	s_lshl_b64 s[6:7], s[6:7], 12
	s_add_u32 s6, s37, s6
	s_addc_u32 s7, s36, s7
	v_mov_b32_e32 v196, v128
	v_mov_b32_e32 v2, v130
	s_barrier
	s_add_i32 s69, s68, 0x18000
	v_lshl_add_u64 v[4:5], s[6:7], 0, v[196:197]
	v_mov_b32_e32 v3, v197
	v_lshl_add_u64 v[4:5], v[4:5], 0, s[94:95]
	s_mov_b32 m0, s69
	v_lshl_add_u64 v[2:3], s[6:7], 0, v[2:3]
	s_add_i32 s70, s68, 0x1a000
	s_lshl_b64 s[8:9], s[8:9], 12
	global_load_lds_dwordx4 v[4:5], off
	v_lshl_add_u64 v[2:3], v[2:3], 0, s[94:95]
	s_mov_b32 m0, s70
	s_add_u32 s8, s67, s8
	global_load_lds_dwordx4 v[2:3], off
	s_addc_u32 s9, s53, s9
	v_mov_b32_e32 v196, v128
	v_mov_b32_e32 v2, v130
	s_add_i32 s71, s68, 0x8000
	v_lshl_add_u64 v[4:5], s[8:9], 0, v[196:197]
	v_mov_b32_e32 v3, v197
	v_lshl_add_u64 v[4:5], v[4:5], 0, s[94:95]
	s_mov_b32 m0, s71
	v_lshl_add_u64 v[2:3], s[8:9], 0, v[2:3]
	s_add_i32 s33, s68, 0xa000
	s_lshl_b64 s[10:11], s[10:11], 12
	global_load_lds_dwordx4 v[4:5], off
	v_lshl_add_u64 v[2:3], v[2:3], 0, s[94:95]
	s_mov_b32 m0, s33
	s_add_u32 s10, s37, s10
	global_load_lds_dwordx4 v[2:3], off
	s_addc_u32 s11, s36, s11
	v_mov_b32_e32 v196, v128
	v_mov_b32_e32 v2, v130
	s_add_i32 s72, s68, 0x1c000
	v_lshl_add_u64 v[4:5], s[10:11], 0, v[196:197]
	v_mov_b32_e32 v3, v197
	v_lshl_add_u64 v[4:5], v[4:5], 0, s[94:95]
	s_mov_b32 m0, s72
	v_lshl_add_u64 v[2:3], s[10:11], 0, v[2:3]
	s_add_i32 s36, s68, 0x1e000
	global_load_lds_dwordx4 v[4:5], off
	v_lshl_add_u64 v[2:3], v[2:3], 0, s[94:95]
	s_mov_b32 m0, s36
	v_and_b32_e32 v6, 15, v132
	global_load_lds_dwordx4 v[2:3], off
	v_lshlrev_b32_e32 v0, 12, v0
	v_and_b32_e32 v7, 48, v132
	v_and_b32_e32 v2, 0x3000, v0
	v_lshlrev_b32_e32 v0, 6, v6
	v_lshlrev_b32_e32 v4, 2, v132
	v_or_b32_e32 v3, v0, v7
	v_and_b32_e32 v4, 32, v4
	s_mov_b32 s10, 0x10000
	v_bitop3_b32 v5, v0, v4, v7 bitop3:0x36
	v_bitop3_b32 v6, v3, s10, v4 bitop3:0xde
	s_mov_b32 s10, 0x14000
	v_lshlrev_b32_e32 v0, 6, v132
	s_waitcnt vmcnt(6)
	v_bitop3_b32 v8, v3, s10, v4 bitop3:0xde
	s_mov_b32 s10, 0x1c000
	v_lshlrev_b32_e32 v1, 13, v1
	v_and_b32_e32 v0, 0x3c0, v0
	v_bitop3_b32 v9, v3, s2, v4 bitop3:0xde
	v_bitop3_b32 v3, v3, s10, v4 bitop3:0xde
	v_bitop3_b32 v4, v0, v4, v7 bitop3:0x36
	v_or_b32_e32 v7, 0x800, v1
	v_or_b32_e32 v10, 0x1000, v1
	v_or_b32_e32 v11, 0x1800, v1
	v_mov_b32_e32 v0, 0
	s_mov_b32 s37, -2
	s_mov_b64 s[10:11], 0
	v_add_u32_e32 v129, v6, v2
	v_add_u32_e32 v136, v5, v1
	v_add_u32_e32 v135, v4, v7
	v_add_u32_e32 v134, v4, v10
	v_add_u32_e32 v133, v4, v11
	v_add_u32_e32 v139, v8, v2
	v_add_u32_e32 v138, v9, v2
	v_add_u32_e32 v137, v3, v2
	v_mov_b32_e32 v1, v0
	v_mov_b32_e32 v2, v0
	v_mov_b32_e32 v3, v0
	v_mov_b32_e32 v4, v0
	v_mov_b32_e32 v5, v0
	v_mov_b32_e32 v6, v0
	v_mov_b32_e32 v7, v0
	v_mov_b32_e32 v8, v0
	v_mov_b32_e32 v9, v0
	v_mov_b32_e32 v10, v0
	v_mov_b32_e32 v11, v0
	v_mov_b32_e32 v12, v0
	v_mov_b32_e32 v13, v0
	v_mov_b32_e32 v14, v0
	v_mov_b32_e32 v15, v0
	v_mov_b32_e32 v16, v0
	v_mov_b32_e32 v17, v0
	v_mov_b32_e32 v18, v0
	v_mov_b32_e32 v19, v0
	v_mov_b32_e32 v20, v0
	v_mov_b32_e32 v21, v0
	v_mov_b32_e32 v22, v0
	v_mov_b32_e32 v23, v0
	v_mov_b32_e32 v24, v0
	v_mov_b32_e32 v25, v0
	v_mov_b32_e32 v26, v0
	v_mov_b32_e32 v27, v0
	v_mov_b32_e32 v28, v0
	v_mov_b32_e32 v29, v0
	v_mov_b32_e32 v30, v0
	v_mov_b32_e32 v31, v0
	v_mov_b32_e32 v32, v0
	v_mov_b32_e32 v33, v0
	v_mov_b32_e32 v34, v0
	v_mov_b32_e32 v35, v0
	v_mov_b32_e32 v36, v0
	v_mov_b32_e32 v37, v0
	v_mov_b32_e32 v38, v0
	v_mov_b32_e32 v39, v0
	v_mov_b32_e32 v40, v0
	v_mov_b32_e32 v41, v0
	v_mov_b32_e32 v42, v0
	v_mov_b32_e32 v43, v0
	v_mov_b32_e32 v44, v0
	v_mov_b32_e32 v45, v0
	v_mov_b32_e32 v46, v0
	v_mov_b32_e32 v47, v0
	v_mov_b32_e32 v48, v0
	v_mov_b32_e32 v49, v0
	v_mov_b32_e32 v50, v0
	v_mov_b32_e32 v51, v0
	v_mov_b32_e32 v52, v0
	v_mov_b32_e32 v53, v0
	v_mov_b32_e32 v54, v0
	v_mov_b32_e32 v55, v0
	v_mov_b32_e32 v56, v0
	v_mov_b32_e32 v57, v0
	v_mov_b32_e32 v58, v0
	v_mov_b32_e32 v59, v0
	v_mov_b32_e32 v60, v0
	v_mov_b32_e32 v61, v0
	v_mov_b32_e32 v62, v0
	v_mov_b32_e32 v63, v0
	v_mov_b32_e32 v64, v0
	v_mov_b32_e32 v65, v0
	v_mov_b32_e32 v66, v0
	v_mov_b32_e32 v67, v0
	v_mov_b32_e32 v68, v0
	v_mov_b32_e32 v69, v0
	v_mov_b32_e32 v70, v0
	v_mov_b32_e32 v71, v0
	v_mov_b32_e32 v72, v0
	v_mov_b32_e32 v73, v0
	v_mov_b32_e32 v74, v0
	v_mov_b32_e32 v75, v0
	v_mov_b32_e32 v76, v0
	v_mov_b32_e32 v77, v0
	v_mov_b32_e32 v78, v0
	v_mov_b32_e32 v79, v0
	v_mov_b32_e32 v80, v0
	v_mov_b32_e32 v81, v0
	v_mov_b32_e32 v82, v0
	v_mov_b32_e32 v83, v0
	v_mov_b32_e32 v84, v0
	v_mov_b32_e32 v85, v0
	v_mov_b32_e32 v86, v0
	v_mov_b32_e32 v87, v0
	v_mov_b32_e32 v88, v0
	v_mov_b32_e32 v89, v0
	v_mov_b32_e32 v90, v0
	v_mov_b32_e32 v91, v0
	v_mov_b32_e32 v92, v0
	v_mov_b32_e32 v93, v0
	v_mov_b32_e32 v94, v0
	v_mov_b32_e32 v95, v0
	v_mov_b32_e32 v96, v0
	v_mov_b32_e32 v97, v0
	v_mov_b32_e32 v98, v0
	v_mov_b32_e32 v99, v0
	v_mov_b32_e32 v100, v0
	v_mov_b32_e32 v101, v0
	v_mov_b32_e32 v102, v0
	v_mov_b32_e32 v103, v0
	v_mov_b32_e32 v104, v0
	v_mov_b32_e32 v105, v0
	v_mov_b32_e32 v106, v0
	v_mov_b32_e32 v107, v0
	v_mov_b32_e32 v108, v0
	v_mov_b32_e32 v109, v0
	v_mov_b32_e32 v110, v0
	v_mov_b32_e32 v111, v0
	v_mov_b32_e32 v112, v0
	v_mov_b32_e32 v113, v0
	v_mov_b32_e32 v114, v0
	v_mov_b32_e32 v115, v0
	v_mov_b32_e32 v116, v0
	v_mov_b32_e32 v117, v0
	v_mov_b32_e32 v118, v0
	v_mov_b32_e32 v119, v0
	v_mov_b32_e32 v120, v0
	v_mov_b32_e32 v121, v0
	v_mov_b32_e32 v122, v0
	v_mov_b32_e32 v123, v0
	v_mov_b32_e32 v124, v0
	v_mov_b32_e32 v125, v0
	v_mov_b32_e32 v126, v0
	v_mov_b32_e32 v127, v0
	s_mov_b64 s[44:45], 0x80080
	s_mov_b64 s[46:47], 0x80100
	s_mov_b64 s[48:49], 0x80180
	s_barrier
	.p2align	6
